# grid barrier: the globally-last XCD leader bumps all 16 per-XCD generation words with one 16-lane atomic (one release hop instead of two for non-leader workgroups)
# baseline (speedup 1.0000x reference)
.LBB0_327:
	s_or_b64 exec, exec, s[12:13]
	s_and_saveexec_b64 s[4:5], s[14:15]
	s_cbranch_execz .LBB0_329
	global_atomic_add v[0:1], v189, off
	v_readfirstlane_b32 s100, v0
	v_readfirstlane_b32 s101, v1
	s_sub_u32 s100, s100, 0x1100
	s_subb_u32 s101, s101, 0
	s_mov_b64 exec, 0xffff
	v_mbcnt_lo_u32_b32 v2, -1, 0
	v_lshlrev_b32_e32 v2, 8, v2
	v_mov_b32_e32 v3, 1
	global_atomic_add v2, v3, s[100:101]
	s_mov_b64 exec, 1
.LBB0_329:
	s_or_b64 exec, exec, s[4:5]
	s_mov_b64 s[4:5], exec
	v_mbcnt_lo_u32_b32 v0, s4, 0
	v_mbcnt_hi_u32_b32 v0, s5, v0
	v_cmp_eq_u32_e32 vcc, 0, v0
	s_waitcnt vmcnt(0)
	s_and_saveexec_b64 s[10:11], vcc
	s_cbranch_execz .LBB0_331
.LBB0_331:
	s_or_b64 exec, exec, s[10:11]
	s_waitcnt vmcnt(0)

.LBB0_432:
	s_or_b64 exec, exec, s[14:15]
	s_and_saveexec_b64 s[4:5], s[16:17]
	s_cbranch_execz .LBB0_434
	global_atomic_add v[0:1], v189, off
	v_readfirstlane_b32 s100, v0
	v_readfirstlane_b32 s101, v1
	s_sub_u32 s100, s100, 0x1100
	s_subb_u32 s101, s101, 0
	s_mov_b64 exec, 0xffff
	v_mbcnt_lo_u32_b32 v2, -1, 0
	v_lshlrev_b32_e32 v2, 8, v2
	v_mov_b32_e32 v3, 1
	global_atomic_add v2, v3, s[100:101]
	s_mov_b64 exec, 1
.LBB0_434:
	s_or_b64 exec, exec, s[4:5]
	s_mov_b64 s[4:5], exec
	v_mbcnt_lo_u32_b32 v0, s4, 0
	v_mbcnt_hi_u32_b32 v0, s5, v0
	v_cmp_eq_u32_e32 vcc, 0, v0
	s_waitcnt vmcnt(0)
	s_and_saveexec_b64 s[12:13], vcc
	s_cbranch_execz .LBB0_436
.LBB0_436:
	s_or_b64 exec, exec, s[12:13]
	s_waitcnt vmcnt(0)

.LBB0_513:
	s_or_b64 exec, exec, s[16:17]
	s_and_saveexec_b64 s[6:7], s[18:19]
	s_cbranch_execz .LBB0_515
	global_atomic_add v[0:1], v189, off
	v_readfirstlane_b32 s100, v0
	v_readfirstlane_b32 s101, v1
	s_sub_u32 s100, s100, 0x1100
	s_subb_u32 s101, s101, 0
	s_mov_b64 exec, 0xffff
	v_mbcnt_lo_u32_b32 v2, -1, 0
	v_lshlrev_b32_e32 v2, 8, v2
	v_mov_b32_e32 v3, 1
	global_atomic_add v2, v3, s[100:101]
	s_mov_b64 exec, 1
.LBB0_515:
	s_or_b64 exec, exec, s[6:7]
	s_mov_b64 s[6:7], exec
	v_mbcnt_lo_u32_b32 v0, s6, 0
	v_mbcnt_hi_u32_b32 v0, s7, v0
	v_cmp_eq_u32_e32 vcc, 0, v0
	s_waitcnt vmcnt(0)
	s_and_saveexec_b64 s[14:15], vcc
	s_cbranch_execz .LBB0_517
.LBB0_517:
	s_or_b64 exec, exec, s[14:15]
	s_waitcnt vmcnt(0)

.LBB0_570:
	s_or_b64 exec, exec, s[12:13]
	s_and_saveexec_b64 s[6:7], s[14:15]
	s_cbranch_execz .LBB0_572
	global_atomic_add v[0:1], v189, off
	v_readfirstlane_b32 s100, v0
	v_readfirstlane_b32 s101, v1
	s_sub_u32 s100, s100, 0x1100
	s_subb_u32 s101, s101, 0
	s_mov_b64 exec, 0xffff
	v_mbcnt_lo_u32_b32 v2, -1, 0
	v_lshlrev_b32_e32 v2, 8, v2
	v_mov_b32_e32 v3, 1
	global_atomic_add v2, v3, s[100:101]
	s_mov_b64 exec, 1
.LBB0_572:
	s_or_b64 exec, exec, s[6:7]
	s_mov_b64 s[6:7], exec
	v_mbcnt_lo_u32_b32 v0, s6, 0
	v_mbcnt_hi_u32_b32 v0, s7, v0
	v_cmp_eq_u32_e32 vcc, 0, v0
	s_waitcnt vmcnt(0)
	s_and_saveexec_b64 s[10:11], vcc
	s_cbranch_execz .LBB0_574
.LBB0_574:
	s_or_b64 exec, exec, s[10:11]
	s_waitcnt vmcnt(0)

.LBB0_970:
	s_or_b64 exec, exec, s[6:7]
	s_mov_b64 s[6:7], exec
	v_mbcnt_lo_u32_b32 v0, s6, 0
	v_mbcnt_hi_u32_b32 v0, s7, v0
	v_cmp_eq_u32_e32 vcc, 0, v0
	s_waitcnt vmcnt(0)
	s_and_saveexec_b64 s[10:11], vcc
	s_cbranch_execz .LBB0_972
.LBB0_972:
	s_or_b64 exec, exec, s[10:11]
	s_waitcnt vmcnt(0)

.LBB0_1140:
	s_or_b64 exec, exec, s[14:15]
	s_and_saveexec_b64 s[6:7], s[16:17]
	s_cbranch_execz .LBB0_1142
	global_atomic_add v[0:1], v189, off
	v_readfirstlane_b32 s100, v0
	v_readfirstlane_b32 s101, v1
	s_sub_u32 s100, s100, 0x1100
	s_subb_u32 s101, s101, 0
	s_mov_b64 exec, 0xffff
	v_mbcnt_lo_u32_b32 v2, -1, 0
	v_lshlrev_b32_e32 v2, 8, v2
	v_mov_b32_e32 v3, 1
	global_atomic_add v2, v3, s[100:101]
	s_mov_b64 exec, 1
.LBB0_1142:
	s_or_b64 exec, exec, s[6:7]
	s_mov_b64 s[6:7], exec
	v_mbcnt_lo_u32_b32 v0, s6, 0
	v_mbcnt_hi_u32_b32 v0, s7, v0
	v_cmp_eq_u32_e32 vcc, 0, v0
	s_waitcnt vmcnt(0)
	s_and_saveexec_b64 s[12:13], vcc
	s_cbranch_execz .LBB0_1144
.LBB0_1144:
	s_or_b64 exec, exec, s[12:13]
	s_waitcnt vmcnt(0)

.LBB0_1218:
	s_or_b64 exec, exec, s[6:7]
	s_mov_b64 s[6:7], exec
	v_mbcnt_lo_u32_b32 v0, s6, 0
	v_mbcnt_hi_u32_b32 v0, s7, v0
	v_cmp_eq_u32_e32 vcc, 0, v0
	s_waitcnt vmcnt(0)
	s_and_saveexec_b64 s[14:15], vcc
	s_cbranch_execz .LBB0_1220
.LBB0_1220:
	s_or_b64 exec, exec, s[14:15]
	s_waitcnt vmcnt(0)

.LBB0_1274:
	s_or_b64 exec, exec, s[6:7]
	s_mov_b64 s[6:7], exec
	v_mbcnt_lo_u32_b32 v0, s6, 0
	v_mbcnt_hi_u32_b32 v0, s7, v0
	v_cmp_eq_u32_e32 vcc, 0, v0
	s_waitcnt vmcnt(0)
	s_and_saveexec_b64 s[12:13], vcc
	s_cbranch_execz .LBB0_333
	s_branch .LBB0_333

	.amdhsa_kernel _Z10fwd_kernel6Params
		.amdhsa_group_segment_fixed_size 0
		.amdhsa_private_segment_fixed_size 0
		.amdhsa_kernarg_size 416
		.amdhsa_user_sgpr_count 2
		.amdhsa_user_sgpr_dispatch_ptr 0
		.amdhsa_user_sgpr_queue_ptr 0
		.amdhsa_user_sgpr_kernarg_segment_ptr 1
		.amdhsa_user_sgpr_dispatch_id 0
		.amdhsa_user_sgpr_kernarg_preload_length 0
		.amdhsa_user_sgpr_kernarg_preload_offset 0
		.amdhsa_user_sgpr_private_segment_size 0
		.amdhsa_uses_dynamic_stack 0
		.amdhsa_enable_private_segment 0
		.amdhsa_system_sgpr_workgroup_id_x 1
		.amdhsa_system_sgpr_workgroup_id_y 0
		.amdhsa_system_sgpr_workgroup_id_z 0
		.amdhsa_system_sgpr_workgroup_info 0
		.amdhsa_system_vgpr_workitem_id 2
		.amdhsa_next_free_vgpr 256
		.amdhsa_next_free_sgpr 102
		.amdhsa_accum_offset 256
		.amdhsa_reserve_vcc 1
		.amdhsa_float_round_mode_32 0
		.amdhsa_float_round_mode_16_64 0
		.amdhsa_float_denorm_mode_32 3
		.amdhsa_float_denorm_mode_16_64 3
		.amdhsa_dx10_clamp 1
		.amdhsa_ieee_mode 1
		.amdhsa_fp16_overflow 0
		.amdhsa_tg_split 0
		.amdhsa_exception_fp_ieee_invalid_op 0
		.amdhsa_exception_fp_denorm_src 0
		.amdhsa_exception_fp_ieee_div_zero 0
		.amdhsa_exception_fp_ieee_overflow 0
		.amdhsa_exception_fp_ieee_underflow 0
		.amdhsa_exception_fp_ieee_inexact 0
		.amdhsa_exception_int_div_zero 0
	.end_amdhsa_kernel

amdhsa.kernels:
  - .agpr_count:     0
    .args:
      - .offset:         0
        .size:           160
        .value_kind:     by_value
      - .offset:         160
        .size:           4
        .value_kind:     hidden_block_count_x
      - .offset:         164
        .size:           4
        .value_kind:     hidden_block_count_y
      - .offset:         168
        .size:           4
        .value_kind:     hidden_block_count_z
      - .offset:         172
        .size:           2
        .value_kind:     hidden_group_size_x
      - .offset:         174
        .size:           2
        .value_kind:     hidden_group_size_y
      - .offset:         176
        .size:           2
        .value_kind:     hidden_group_size_z
      - .offset:         178
        .size:           2
        .value_kind:     hidden_remainder_x
      - .offset:         180
        .size:           2
        .value_kind:     hidden_remainder_y
      - .offset:         182
        .size:           2
        .value_kind:     hidden_remainder_z
      - .offset:         200
        .size:           8
        .value_kind:     hidden_global_offset_x
      - .offset:         208
        .size:           8
        .value_kind:     hidden_global_offset_y
      - .offset:         216
        .size:           8
        .value_kind:     hidden_global_offset_z
      - .offset:         224
        .size:           2
        .value_kind:     hidden_grid_dims
      - .offset:         248
        .size:           8
        .value_kind:     hidden_multigrid_sync_arg
      - .offset:         280
        .size:           4
        .value_kind:     hidden_dynamic_lds_size
    .group_segment_fixed_size: 0
    .kernarg_segment_align: 8
    .kernarg_segment_size: 416
    .language:       OpenCL C
    .language_version:
      - 2
      - 0
    .max_flat_workgroup_size: 512
    .name:           _Z10fwd_kernel6Params
    .private_segment_fixed_size: 0
    .sgpr_count:     108
    .sgpr_spill_count: 37
    .symbol:         _Z10fwd_kernel6Params.kd
    .uniform_work_group_size: 1
    .uses_dynamic_stack: false
    .vgpr_count:     256
    .vgpr_spill_count: 0
    .wavefront_size: 64
